# skinny_branch task: gate rows and all 8 weight fragments loaded up front, LDS operands double-buffered, epilogue no longer waits on serialized loads
# speedup vs baseline: 1.0051x; 1.0051x over previous
; #define LAS __attribute__((address_space(3)))
; __device__ __forceinline__ u32x2 pack4(const f32x4& v) { u32x2 w; w.x = pk2(v[0], v[1]); w.y = pk2(v[2], v[3]); return w; }
; __device__ __forceinline__ f32x4 unpack4(const u32x2& x) { return (f32x4){bf2f(x.x & 0xffffu), __uint_as_float(x.x & 0xffff0000u), bf2f(x.y & 0xffffu), __uint_as_float(x.y & 0xffff0000u)}; }
; __device__ __forceinline__ void skinny_branch(Frame& F, int l) {
;     ...
;         const int z = task >> 6, tile = F.wave & 1, kq = F.wave >> 1, n0 = (task & 63) * 32 + tile * 16; f32x4 d[2];
;         __syncthreads();
;         if (z == 1) skinny_stage_att(F);
;         else skinny_stage<1024>(F.lds, (const bf16_t*)(F.ws + WS_ABR) + (size_t)z * MPAD * 1024 + (size_t)MPT * 1024, 1024, F.tid);
;         skinny_tile<1024>(F.lds, W + (size_t)z * 2048 * 1024 + kq * 256, 1024, n0, kq * 256, 256, F.lane, d[0], d[1]);
;         __syncthreads();
;         LAS f32x4* red = (LAS f32x4*)F.lds;
;         red[(F.wave * 2 + 0) * 64 + F.lane] = d[0]; red[(F.wave * 2 + 1) * 64 + F.lane] = d[1];
;         __syncthreads();
;         if (kq == 0) { const int col = n0 + 4 * (F.lane >> 4);
; #pragma unroll
;             for (int tt = 0; tt < 2; ++tt) { const int t = 16 * tt + (F.lane & 15), row = MPT + t; f32x4 a = d[tt];
; #pragma unroll
;                 for (int k2 = 1; k2 < 4; ++k2) a += red[((2 * k2 + tile) * 2 + tt) * 64 + F.lane];
;                 const f32x4 gm = unpack4(*(const u32x2*)(P + (size_t)row * NPROJ + C_MG + z * 2048 + col));
;                 *(u32x2*)(brp + ((size_t)z * 32 + t) * DM + col) = pack4(a * gm); } }
.LBB0_1331:
	s_lshl_b32 s24, s17, 5
	s_and_b32 s24, s24, 0x7e0
	s_or_b32 s24, s24, s16
	s_lshl_b64 s[26:27], s[22:23], 22
	s_add_u32 s26, s4, s26
	v_or_b32_e32 v2, s24, v15
	s_addc_u32 s27, s14, s27
	v_lshlrev_b32_e32 v98, 11, v2
	v_lshl_add_u64 v[2:3], s[26:27], 0, v[98:99]
	v_mov_b32_e32 v29, v99
	v_lshl_add_u64 v[34:35], v[2:3], 0, v[28:29]
	v_or_b32_e32 v136, s24, v37
	s_lshl_b32 s28, s40, 12
	v_lshlrev_b32_e32 v136, 1, v136
	s_mov_b32 s29, 0
	v_mov_b32_e32 v137, v99
	v_lshl_add_u64 v[138:139], v[16:17], 0, s[28:29]
	v_lshl_add_u64 v[140:141], v[18:19], 0, s[28:29]
	v_lshl_add_u64 v[138:139], v[138:139], 0, v[136:137]
	v_lshl_add_u64 v[140:141], v[140:141], 0, v[136:137]
	global_load_dwordx2 v[132:133], v[138:139], off
	global_load_dwordx2 v[134:135], v[140:141], off
	global_load_dwordx4 v[100:103], v[34:35], off
	global_load_dwordx4 v[104:107], v[34:35], off offset:16
	global_load_dwordx4 v[108:111], v[34:35], off offset:32
	global_load_dwordx4 v[112:115], v[34:35], off offset:48
	global_load_dwordx4 v[116:119], v[34:35], off offset:256
	global_load_dwordx4 v[120:123], v[34:35], off offset:272
	global_load_dwordx4 v[124:127], v[34:35], off offset:288
	global_load_dwordx4 v[128:131], v[34:35], off offset:304
	ds_read_b128 v[44:47], v42
	ds_read_b128 v[48:51], v42 offset:33024
	s_andn2_b64 vcc, exec, s[20:21]
	ds_read_b128 v[52:55], v42 offset:16
	ds_read_b128 v[56:59], v42 offset:33040
	s_waitcnt vmcnt(7) lgkmcnt(2)
	v_mfma_f32_16x16x32_bf16 v[6:9], v[100:103], v[44:47], 0
	v_mfma_f32_16x16x32_bf16 v[2:5], v[100:103], v[48:51], 0
	ds_read_b128 v[44:47], v42 offset:32
	ds_read_b128 v[48:51], v42 offset:33056
	s_waitcnt vmcnt(6) lgkmcnt(2)
	v_mfma_f32_16x16x32_bf16 v[6:9], v[104:107], v[52:55], v[6:9]
	v_mfma_f32_16x16x32_bf16 v[2:5], v[104:107], v[56:59], v[2:5]
	ds_read_b128 v[52:55], v42 offset:48
	ds_read_b128 v[56:59], v42 offset:33072
	s_waitcnt vmcnt(5) lgkmcnt(2)
	v_mfma_f32_16x16x32_bf16 v[6:9], v[108:111], v[44:47], v[6:9]
	v_mfma_f32_16x16x32_bf16 v[2:5], v[108:111], v[48:51], v[2:5]
	ds_read_b128 v[44:47], v42 offset:256
	ds_read_b128 v[48:51], v42 offset:33280
	s_waitcnt vmcnt(4) lgkmcnt(2)
	v_mfma_f32_16x16x32_bf16 v[6:9], v[112:115], v[52:55], v[6:9]
	v_mfma_f32_16x16x32_bf16 v[2:5], v[112:115], v[56:59], v[2:5]
	ds_read_b128 v[52:55], v42 offset:272
	ds_read_b128 v[56:59], v42 offset:33296
	s_waitcnt vmcnt(3) lgkmcnt(2)
	v_mfma_f32_16x16x32_bf16 v[6:9], v[116:119], v[44:47], v[6:9]
	v_mfma_f32_16x16x32_bf16 v[2:5], v[116:119], v[48:51], v[2:5]
	ds_read_b128 v[44:47], v42 offset:288
	ds_read_b128 v[48:51], v42 offset:33312
	s_waitcnt vmcnt(2) lgkmcnt(2)
	v_mfma_f32_16x16x32_bf16 v[6:9], v[120:123], v[52:55], v[6:9]
	v_mfma_f32_16x16x32_bf16 v[2:5], v[120:123], v[56:59], v[2:5]
	ds_read_b128 v[52:55], v42 offset:304
	ds_read_b128 v[56:59], v42 offset:33328
	s_waitcnt vmcnt(1) lgkmcnt(2)
	v_mfma_f32_16x16x32_bf16 v[6:9], v[124:127], v[44:47], v[6:9]
	v_mfma_f32_16x16x32_bf16 v[2:5], v[124:127], v[48:51], v[2:5]
	s_waitcnt vmcnt(0) lgkmcnt(0)
	s_barrier
	v_mfma_f32_16x16x32_bf16 v[6:9], v[128:131], v[52:55], v[6:9]
	v_mfma_f32_16x16x32_bf16 v[2:5], v[128:131], v[56:59], v[2:5]
	s_nop 6
	ds_write_b128 v36, v[6:9]
	ds_write_b128 v36, v[2:5] offset:1024
	s_waitcnt lgkmcnt(0)
	s_barrier
	s_cbranch_vccnz .LBB0_1312
	ds_read_b128 v[44:47], v43 offset:4096
	v_or_b32_e32 v27, s24, v37
	s_lshl_b32 s24, s40, 11
	s_ashr_i32 s25, s24, 31
	s_lshl_b64 s[22:23], s[22:23], 17
	s_waitcnt lgkmcnt(0)
	v_pk_add_f32 v[46:47], v[8:9], v[46:47]
	v_pk_add_f32 v[44:45], v[6:7], v[44:45]
	ds_read_b128 v[6:9], v43 offset:8192
	s_add_u32 s22, s8, s22
	s_addc_u32 s23, s15, s23
	v_lshlrev_b32_e32 v98, 1, v27
	v_lshl_add_u64 v[34:35], s[22:23], 0, v[98:99]
	s_waitcnt lgkmcnt(0)
	v_pk_add_f32 v[46:47], v[46:47], v[8:9]
	v_pk_add_f32 v[44:45], v[44:45], v[6:7]
	ds_read_b128 v[6:9], v43 offset:12288
	s_lshl_b64 s[22:23], s[24:25], 1
	v_mov_b32_e32 v31, v99
	v_mov_b32_e32 v33, v99
	s_waitcnt lgkmcnt(0)
	v_pk_add_f32 v[6:7], v[44:45], v[6:7]
	v_mov_b32_e32 v44, v132
	v_mov_b32_e32 v45, v133
	v_pk_add_f32 v[8:9], v[46:47], v[8:9]
	s_waitcnt vmcnt(0)
	v_lshlrev_b32_e32 v46, 16, v44
	v_and_b32_e32 v47, 0xffff0000, v44
	v_lshlrev_b32_e32 v44, 16, v45
	v_and_b32_e32 v45, 0xffff0000, v45
	v_pk_mul_f32 v[8:9], v[8:9], v[44:45]
	v_pk_mul_f32 v[6:7], v[6:7], v[46:47]
	s_nop 0
	v_cvt_pk_bf16_f32 v6, v6, v7
	v_cvt_pk_bf16_f32 v7, v8, v9
	v_lshl_add_u64 v[8:9], v[34:35], 0, v[30:31]
	global_store_dwordx2 v[8:9], v[6:7], off
	ds_read_b128 v[6:9], v43 offset:5120
	s_waitcnt lgkmcnt(0)
	v_pk_add_f32 v[8:9], v[4:5], v[8:9]
	v_pk_add_f32 v[6:7], v[2:3], v[6:7]
	ds_read_b128 v[2:5], v43 offset:9216
	s_waitcnt lgkmcnt(0)
	v_pk_add_f32 v[8:9], v[8:9], v[4:5]
	v_pk_add_f32 v[6:7], v[6:7], v[2:3]
	ds_read_b128 v[2:5], v43 offset:13312
	s_waitcnt lgkmcnt(0)
	v_pk_add_f32 v[2:3], v[6:7], v[2:3]
	v_mov_b32_e32 v6, v134
	v_mov_b32_e32 v7, v135
	v_pk_add_f32 v[4:5], v[8:9], v[4:5]
	v_lshlrev_b32_e32 v8, 16, v6
	v_and_b32_e32 v9, 0xffff0000, v6
	v_lshlrev_b32_e32 v6, 16, v7
	v_and_b32_e32 v7, 0xffff0000, v7
	v_pk_mul_f32 v[4:5], v[4:5], v[6:7]
	v_pk_mul_f32 v[2:3], v[2:3], v[8:9]
	s_nop 0
	v_cvt_pk_bf16_f32 v2, v2, v3
	v_cvt_pk_bf16_f32 v3, v4, v5
	v_lshl_add_u64 v[4:5], v[34:35], 0, v[32:33]
	global_store_dwordx2 v[4:5], v[2:3], off
	s_branch .LBB0_1312
